# speedup vs baseline: 1.0070x; 1.0070x over previous
; #define PG8_STAGE(bufoff, gbase, voff) do { _Pragma("unroll") for (int _i = 0; _i < 2; ++_i) \
;         __builtin_amdgcn_global_load_lds((const unsigned*)((const char*)(gbase) + (voff)[_i]), (LAS unsigned*)(lds + (bufoff) + ldsw + _i * 8192), 16, 0, 0); } while (0)
; #define PG8_LDA(dst, b, h) do { _Pragma("unroll") for (int m = 0; m < 4; ++m) _Pragma("unroll") for (int k = 0; k < 2; ++k) dst[m][k] = *(const LAS bf16x8*)(lds + PG8_SA(b, h) + aoff + m * 2048 + k * 1024); } while (0)
; #define PG8_LDB(dst, b, h) do { _Pragma("unroll") for (int n = 0; n < 2; ++n) _Pragma("unroll") for (int k = 0; k < 2; ++k) dst[n][k] = *(const LAS bf16x8*)(lds + PG8_SB(b, h) + boff + n * 2048 + k * 1024); } while (0)
; #define PG8_WAIT_V(n) asm volatile("s_waitcnt vmcnt(" #n ")" ::: "memory")
; #define PG8_WAIT_L(n) asm volatile("s_waitcnt lgkmcnt(" #n ")" ::: "memory")
; #define PG8_BAR __builtin_amdgcn_s_barrier()
; #define PG8_SCHED __builtin_amdgcn_sched_barrier(0)
; template <class Epi, class Sched, bool FUSED = false, bool APERM = false>
; __device__ __forceinline__ void gemm_phase(int wid_s, LAS unsigned char* lds, const Gemm g, const Sched& S, const Epi& E) {
;     ...
;         for (int t = 0; t < nt; t += 2) {
;             const bool last = (t == nt - 2);
;             const char* a1 = cA + (size_t)(t + 1) * kstep;
;             const char* a2 = last ? nA : cA + (size_t)(t + 2) * kstep; const char* b2 = last ? nB : cB + (size_t)(t + 2) * kstep;
;             const char* a3 = a2 + kstep; const char* b3 = b2 + kstep;
;             if (last && has_next) S.a_ready(nxt);
;             PG8_LDB(B0, 0, 0); PG8_LDB(B1, 0, 1); PG8_SCHED; PG8_LDA(At, 0, 0); PG8_STAGE(PG8_SA(1, 1), a1 + hstep, voffA);
;             PG8_WAIT_V(8); PG8_WAIT_L(0); PG8_BAR; PG8_MMA(0, 0, At, B0); PG8_MMA(0, 1, At, B1); PG8_BAR; PG8_SCHED;
;             PG8_LDA(At, 0, 1); PG8_STAGE(PG8_SB(0, 0), b2, voffB); PG8_STAGE(PG8_SB(0, 1), b2 + hstep, voffB); PG8_STAGE(PG8_SA(0, 0), a2, voffA);
;             PG8_WAIT_V(8); PG8_WAIT_L(0); PG8_BAR; PG8_MMA(1, 0, At, B0); PG8_MMA(1, 1, At, B1); PG8_BAR; PG8_SCHED;
.LBB0_342:
	s_add_u32 s38, s36, 0xfff80080
	s_addc_u32 s39, s37, -1
	s_add_i32 s64, 0, 0x10000
	s_cmp_eq_u32 s63, 28
	s_cselect_b32 s41, s1, s39
	s_cselect_b32 s40, s23, s38
	s_cselect_b32 s39, s25, s62
	s_cselect_b32 s38, s35, s61
	s_add_i32 s66, 0, 0x14000
	v_add_u32_e32 v144, s64, v227
	v_add_u32_e32 v160, s66, v227
	ds_read_b128 v[132:135], v144
	ds_read_b128 v[136:139], v144 offset:1024
	ds_read_b128 v[140:143], v144 offset:2048
	ds_read_b128 v[144:147], v144 offset:3072
	ds_read_b128 v[148:151], v160
	ds_read_b128 v[152:155], v160 offset:1024
	ds_read_b128 v[156:159], v160 offset:2048
	ds_read_b128 v[160:163], v160 offset:3072
	v_lshl_add_u64 v[214:215], s[36:37], 0, v[212:213]
	s_add_i32 m0, s48, 0xc000
	ds_read_b128 v[164:167], v228
	ds_read_b128 v[168:171], v228 offset:1024
	ds_read_b128 v[172:175], v228 offset:2048
	ds_read_b128 v[176:179], v228 offset:3072
	ds_read_b128 v[180:183], v228 offset:4096
	ds_read_b128 v[184:187], v228 offset:5120
	ds_read_b128 v[188:191], v228 offset:6144
	ds_read_b128 v[192:195], v228 offset:7168
	global_load_lds_dwordx4 v[214:215], off
	s_add_i32 m0, s48, 0xe000
	v_lshl_add_u64 v[214:215], s[36:37], 0, v[210:211]
	global_load_lds_dwordx4 v[214:215], off
	s_waitcnt vmcnt(8)
	s_waitcnt lgkmcnt(0)
	v_mfma_f32_16x16x32_f16 v[128:131], v[132:135], v[164:167], v[128:131]
	v_mfma_f32_16x16x32_f16 v[124:127], v[140:143], v[164:167], v[124:127]
	v_mfma_f32_16x16x32_f16 v[112:115], v[132:135], v[172:175], v[112:115]
	v_mfma_f32_16x16x32_f16 v[108:111], v[140:143], v[172:175], v[108:111]
	s_barrier
	s_setprio 1
	v_mfma_f32_16x16x32_f16 v[96:99], v[132:135], v[180:183], v[96:99]
	v_mfma_f32_16x16x32_f16 v[92:95], v[140:143], v[180:183], v[92:95]
	v_mfma_f32_16x16x32_f16 v[80:83], v[132:135], v[188:191], v[80:83]
	v_mfma_f32_16x16x32_f16 v[76:79], v[140:143], v[188:191], v[76:79]
	v_mfma_f32_16x16x32_f16 v[128:131], v[136:139], v[168:171], v[128:131]
	v_mfma_f32_16x16x32_f16 v[124:127], v[144:147], v[168:171], v[124:127]
	v_mfma_f32_16x16x32_f16 v[112:115], v[136:139], v[176:179], v[112:115]
	v_mfma_f32_16x16x32_f16 v[108:111], v[144:147], v[176:179], v[108:111]
	v_mfma_f32_16x16x32_f16 v[96:99], v[136:139], v[184:187], v[96:99]
	v_mfma_f32_16x16x32_f16 v[92:95], v[144:147], v[184:187], v[92:95]
	v_mfma_f32_16x16x32_f16 v[80:83], v[136:139], v[192:195], v[80:83]
	v_mfma_f32_16x16x32_f16 v[76:79], v[144:147], v[192:195], v[76:79]
	v_mfma_f32_16x16x32_f16 v[120:123], v[148:151], v[164:167], v[120:123]
	v_mfma_f32_16x16x32_f16 v[116:119], v[156:159], v[164:167], v[116:119]
	v_mfma_f32_16x16x32_f16 v[104:107], v[148:151], v[172:175], v[104:107]
	v_mfma_f32_16x16x32_f16 v[100:103], v[156:159], v[172:175], v[100:103]
	v_mfma_f32_16x16x32_f16 v[88:91], v[148:151], v[180:183], v[88:91]
	v_mfma_f32_16x16x32_f16 v[84:87], v[156:159], v[180:183], v[84:87]
	v_mfma_f32_16x16x32_f16 v[68:71], v[148:151], v[188:191], v[68:71]
	v_mfma_f32_16x16x32_f16 v[72:75], v[156:159], v[188:191], v[72:75]
	v_mfma_f32_16x16x32_f16 v[120:123], v[152:155], v[168:171], v[120:123]
	v_mfma_f32_16x16x32_f16 v[116:119], v[160:163], v[168:171], v[116:119]
	v_mfma_f32_16x16x32_f16 v[104:107], v[152:155], v[176:179], v[104:107]
	v_mfma_f32_16x16x32_f16 v[100:103], v[160:163], v[176:179], v[100:103]
	v_mfma_f32_16x16x32_f16 v[88:91], v[152:155], v[184:187], v[88:91]
	v_mfma_f32_16x16x32_f16 v[84:87], v[160:163], v[184:187], v[84:87]
	v_mfma_f32_16x16x32_f16 v[68:71], v[152:155], v[192:195], v[68:71]
	v_mfma_f32_16x16x32_f16 v[72:75], v[160:163], v[192:195], v[72:75]
	s_setprio 0
	s_barrier
	s_add_i32 s64, s64, s47
	v_lshl_add_u64 v[214:215], s[38:39], 0, v[0:1]
	s_mov_b32 m0, s64
	ds_read_b128 v[164:167], v228 offset:16384
	ds_read_b128 v[168:171], v228 offset:17408
	ds_read_b128 v[172:175], v228 offset:18432
	ds_read_b128 v[176:179], v228 offset:19456
	ds_read_b128 v[180:183], v228 offset:20480
	ds_read_b128 v[184:187], v228 offset:21504
	ds_read_b128 v[188:191], v228 offset:22528
	ds_read_b128 v[192:195], v228 offset:23552
	global_load_lds_dwordx4 v[214:215], off
	s_add_i32 m0, s64, 0x2000
	s_add_u32 s64, s38, 0x80000
	v_lshl_add_u64 v[216:217], s[38:39], 0, v[208:209]
	s_addc_u32 s65, s39, 0
	s_add_i32 s66, s66, s47
	global_load_lds_dwordx4 v[216:217], off
	v_lshl_add_u64 v[218:219], s[64:65], 0, v[0:1]
	s_mov_b32 m0, s66
	v_lshl_add_u64 v[220:221], s[40:41], 0, v[208:209]
	global_load_lds_dwordx4 v[218:219], off
	s_add_i32 m0, s66, 0x2000
	v_lshl_add_u64 v[218:219], s[64:65], 0, v[208:209]
	global_load_lds_dwordx4 v[218:219], off
	s_mov_b32 m0, s48
	v_lshl_add_u64 v[218:219], s[40:41], 0, v[0:1]
	global_load_lds_dwordx4 v[218:219], off
	s_mov_b32 m0, s49
	s_nop 0
	global_load_lds_dwordx4 v[220:221], off
	s_waitcnt vmcnt(8)
	s_waitcnt lgkmcnt(0)
	v_mfma_f32_16x16x32_f16 v[64:67], v[132:135], v[164:167], v[64:67]
	v_mfma_f32_16x16x32_f16 v[60:63], v[140:143], v[164:167], v[60:63]
	v_mfma_f32_16x16x32_f16 v[48:51], v[132:135], v[172:175], v[48:51]
	v_mfma_f32_16x16x32_f16 v[44:47], v[140:143], v[172:175], v[44:47]
	s_barrier
; #define PG8_STAGE(bufoff, gbase, voff) do { _Pragma("unroll") for (int _i = 0; _i < 2; ++_i) \
;         __builtin_amdgcn_global_load_lds((const unsigned*)((const char*)(gbase) + (voff)[_i]), (LAS unsigned*)(lds + (bufoff) + ldsw + _i * 8192), 16, 0, 0); } while (0)
; #define PG8_LDA(dst, b, h) do { _Pragma("unroll") for (int m = 0; m < 4; ++m) _Pragma("unroll") for (int k = 0; k < 2; ++k) dst[m][k] = *(const LAS bf16x8*)(lds + PG8_SA(b, h) + aoff + m * 2048 + k * 1024); } while (0)
; #define PG8_LDB(dst, b, h) do { _Pragma("unroll") for (int n = 0; n < 2; ++n) _Pragma("unroll") for (int k = 0; k < 2; ++k) dst[n][k] = *(const LAS bf16x8*)(lds + PG8_SB(b, h) + boff + n * 2048 + k * 1024); } while (0)
; #define PG8_WAIT_V(n) asm volatile("s_waitcnt vmcnt(" #n ")" ::: "memory")
; #define PG8_WAIT_L(n) asm volatile("s_waitcnt lgkmcnt(" #n ")" ::: "memory")
; #define PG8_BAR __builtin_amdgcn_s_barrier()
; #define PG8_SCHED __builtin_amdgcn_sched_barrier(0)
; template <class Epi, class Sched, bool FUSED = false, bool APERM = false>
; __device__ __forceinline__ void gemm_phase(int wid_s, LAS unsigned char* lds, const Gemm g, const Sched& S, const Epi& E) {
;     ...
;             PG8_WAIT_V(8); PG8_WAIT_L(0); PG8_BAR; PG8_MMA(1, 0, At, B0); PG8_MMA(1, 1, At, B1); PG8_BAR; PG8_SCHED;
;             PG8_LDB(B0, 1, 0); PG8_LDB(B1, 1, 1); PG8_SCHED; PG8_LDA(At, 1, 0); PG8_STAGE(PG8_SA(0, 1), a2 + hstep, voffA);
;             PG8_WAIT_V(8); PG8_WAIT_L(0); PG8_BAR; PG8_MMA(0, 0, At, B0); PG8_MMA(0, 1, At, B1); PG8_BAR; PG8_SCHED;
	s_setprio 1
	v_mfma_f32_16x16x32_f16 v[32:35], v[132:135], v[180:183], v[32:35]
	v_mfma_f32_16x16x32_f16 v[28:31], v[140:143], v[180:183], v[28:31]
	v_mfma_f32_16x16x32_f16 v[12:15], v[132:135], v[188:191], v[12:15]
	v_mfma_f32_16x16x32_f16 v[16:19], v[140:143], v[188:191], v[16:19]
	v_mfma_f32_16x16x32_f16 v[64:67], v[136:139], v[168:171], v[64:67]
	v_mfma_f32_16x16x32_f16 v[60:63], v[144:147], v[168:171], v[60:63]
	v_mfma_f32_16x16x32_f16 v[48:51], v[136:139], v[176:179], v[48:51]
	v_mfma_f32_16x16x32_f16 v[44:47], v[144:147], v[176:179], v[44:47]
	v_mfma_f32_16x16x32_f16 v[32:35], v[136:139], v[184:187], v[32:35]
	v_mfma_f32_16x16x32_f16 v[28:31], v[144:147], v[184:187], v[28:31]
	v_mfma_f32_16x16x32_f16 v[12:15], v[136:139], v[192:195], v[12:15]
	v_mfma_f32_16x16x32_f16 v[16:19], v[144:147], v[192:195], v[16:19]
	v_mfma_f32_16x16x32_f16 v[56:59], v[148:151], v[164:167], v[56:59]
	v_mfma_f32_16x16x32_f16 v[52:55], v[156:159], v[164:167], v[52:55]
	v_mfma_f32_16x16x32_f16 v[40:43], v[148:151], v[172:175], v[40:43]
	v_mfma_f32_16x16x32_f16 v[36:39], v[156:159], v[172:175], v[36:39]
	v_mfma_f32_16x16x32_f16 v[24:27], v[148:151], v[180:183], v[24:27]
	v_mfma_f32_16x16x32_f16 v[20:23], v[156:159], v[180:183], v[20:23]
	v_mfma_f32_16x16x32_f16 v[4:7], v[148:151], v[188:191], v[4:7]
	v_mfma_f32_16x16x32_f16 v[8:11], v[156:159], v[188:191], v[8:11]
	v_mfma_f32_16x16x32_f16 v[56:59], v[152:155], v[168:171], v[56:59]
	v_mfma_f32_16x16x32_f16 v[52:55], v[160:163], v[168:171], v[52:55]
	v_mfma_f32_16x16x32_f16 v[40:43], v[152:155], v[176:179], v[40:43]
	v_mfma_f32_16x16x32_f16 v[36:39], v[160:163], v[176:179], v[36:39]
	v_mfma_f32_16x16x32_f16 v[24:27], v[152:155], v[184:187], v[24:27]
	v_mfma_f32_16x16x32_f16 v[20:23], v[160:163], v[184:187], v[20:23]
	v_mfma_f32_16x16x32_f16 v[4:7], v[152:155], v[192:195], v[4:7]
	v_mfma_f32_16x16x32_f16 v[8:11], v[160:163], v[192:195], v[8:11]
	s_setprio 0
	s_barrier
	s_add_i32 s64, 0, 0x18000
	s_add_i32 s65, 0, 0x1c000
	v_add_u32_e32 v144, s64, v227
	v_add_u32_e32 v160, s65, v227
	ds_read_b128 v[132:135], v144
	ds_read_b128 v[136:139], v144 offset:1024
	ds_read_b128 v[140:143], v144 offset:2048
	ds_read_b128 v[144:147], v144 offset:3072
	ds_read_b128 v[148:151], v160
	ds_read_b128 v[152:155], v160 offset:1024
	ds_read_b128 v[156:159], v160 offset:2048
	ds_read_b128 v[160:163], v160 offset:3072
	s_add_u32 s40, s40, 0x80000
	s_addc_u32 s41, s41, 0
	s_mov_b32 m0, s50
	v_lshl_add_u64 v[222:223], s[40:41], 0, v[0:1]
	ds_read_b128 v[164:167], v228 offset:32768
	ds_read_b128 v[168:171], v228 offset:33792
	ds_read_b128 v[172:175], v228 offset:34816
	ds_read_b128 v[176:179], v228 offset:35840
	ds_read_b128 v[180:183], v228 offset:36864
	ds_read_b128 v[184:187], v228 offset:37888
	ds_read_b128 v[188:191], v228 offset:38912
	ds_read_b128 v[192:195], v228 offset:39936
	global_load_lds_dwordx4 v[222:223], off
	s_mov_b32 m0, s51
	v_lshl_add_u64 v[222:223], s[40:41], 0, v[208:209]
	global_load_lds_dwordx4 v[222:223], off
	s_waitcnt vmcnt(8)
	s_waitcnt lgkmcnt(0)
	v_mfma_f32_16x16x32_f16 v[128:131], v[132:135], v[164:167], v[128:131]
	v_mfma_f32_16x16x32_f16 v[124:127], v[140:143], v[164:167], v[124:127]
	v_mfma_f32_16x16x32_f16 v[112:115], v[132:135], v[172:175], v[112:115]
	v_mfma_f32_16x16x32_f16 v[108:111], v[140:143], v[172:175], v[108:111]
	s_barrier
	s_setprio 1
	v_mfma_f32_16x16x32_f16 v[96:99], v[132:135], v[180:183], v[96:99]
	v_mfma_f32_16x16x32_f16 v[92:95], v[140:143], v[180:183], v[92:95]
	v_mfma_f32_16x16x32_f16 v[80:83], v[132:135], v[188:191], v[80:83]
	v_mfma_f32_16x16x32_f16 v[76:79], v[140:143], v[188:191], v[76:79]
	v_mfma_f32_16x16x32_f16 v[128:131], v[136:139], v[168:171], v[128:131]
	v_mfma_f32_16x16x32_f16 v[124:127], v[144:147], v[168:171], v[124:127]
	v_mfma_f32_16x16x32_f16 v[112:115], v[136:139], v[176:179], v[112:115]
	v_mfma_f32_16x16x32_f16 v[108:111], v[144:147], v[176:179], v[108:111]
	v_mfma_f32_16x16x32_f16 v[96:99], v[136:139], v[184:187], v[96:99]
	v_mfma_f32_16x16x32_f16 v[92:95], v[144:147], v[184:187], v[92:95]
	v_mfma_f32_16x16x32_f16 v[80:83], v[136:139], v[192:195], v[80:83]
	v_mfma_f32_16x16x32_f16 v[76:79], v[144:147], v[192:195], v[76:79]
	v_mfma_f32_16x16x32_f16 v[120:123], v[148:151], v[164:167], v[120:123]
	v_mfma_f32_16x16x32_f16 v[116:119], v[156:159], v[164:167], v[116:119]
	v_mfma_f32_16x16x32_f16 v[104:107], v[148:151], v[172:175], v[104:107]
	v_mfma_f32_16x16x32_f16 v[100:103], v[156:159], v[172:175], v[100:103]
	v_mfma_f32_16x16x32_f16 v[88:91], v[148:151], v[180:183], v[88:91]
	v_mfma_f32_16x16x32_f16 v[84:87], v[156:159], v[180:183], v[84:87]
	v_mfma_f32_16x16x32_f16 v[68:71], v[148:151], v[188:191], v[68:71]
	v_mfma_f32_16x16x32_f16 v[72:75], v[156:159], v[188:191], v[72:75]
	v_mfma_f32_16x16x32_f16 v[120:123], v[152:155], v[168:171], v[120:123]
	v_mfma_f32_16x16x32_f16 v[116:119], v[160:163], v[168:171], v[116:119]
	v_mfma_f32_16x16x32_f16 v[104:107], v[152:155], v[176:179], v[104:107]
	v_mfma_f32_16x16x32_f16 v[100:103], v[160:163], v[176:179], v[100:103]
	v_mfma_f32_16x16x32_f16 v[88:91], v[152:155], v[184:187], v[88:91]
	v_mfma_f32_16x16x32_f16 v[84:87], v[160:163], v[184:187], v[84:87]
	v_mfma_f32_16x16x32_f16 v[68:71], v[152:155], v[192:195], v[68:71]
	v_mfma_f32_16x16x32_f16 v[72:75], v[160:163], v[192:195], v[72:75]
	s_setprio 0
	s_barrier
; #define PG8_STAGE(bufoff, gbase, voff) do { _Pragma("unroll") for (int _i = 0; _i < 2; ++_i) \
;         __builtin_amdgcn_global_load_lds((const unsigned*)((const char*)(gbase) + (voff)[_i]), (LAS unsigned*)(lds + (bufoff) + ldsw + _i * 8192), 16, 0, 0); } while (0)
; #define PG8_LDA(dst, b, h) do { _Pragma("unroll") for (int m = 0; m < 4; ++m) _Pragma("unroll") for (int k = 0; k < 2; ++k) dst[m][k] = *(const LAS bf16x8*)(lds + PG8_SA(b, h) + aoff + m * 2048 + k * 1024); } while (0)
; #define PG8_WAIT_V(n) asm volatile("s_waitcnt vmcnt(" #n ")" ::: "memory")
; #define PG8_WAIT_L(n) asm volatile("s_waitcnt lgkmcnt(" #n ")" ::: "memory")
; #define PG8_BAR __builtin_amdgcn_s_barrier()
; #define PG8_SCHED __builtin_amdgcn_sched_barrier(0)
; template <class Epi, class Sched, bool FUSED = false, bool APERM = false>
; __device__ __forceinline__ void gemm_phase(int wid_s, LAS unsigned char* lds, const Gemm g, const Sched& S, const Epi& E) {
;     ...
;             PG8_LDA(At, 1, 1); PG8_STAGE(PG8_SB(1, 0), b3, voffB); PG8_STAGE(PG8_SB(1, 1), b3 + hstep, voffB); PG8_STAGE(PG8_SA(1, 0), a3, voffA);
;             PG8_WAIT_V(8); PG8_WAIT_L(0); PG8_BAR; PG8_MMA(1, 0, At, B0); PG8_MMA(1, 1, At, B1); PG8_BAR; PG8_SCHED;
;         }
	s_add_i32 s40, s64, s47
	v_lshl_add_u64 v[214:215], v[214:215], 0, s[12:13]
	s_mov_b32 m0, s40
	ds_read_b128 v[164:167], v228 offset:49152
	ds_read_b128 v[168:171], v228 offset:50176
	ds_read_b128 v[172:175], v228 offset:51200
	ds_read_b128 v[176:179], v228 offset:52224
	ds_read_b128 v[180:183], v228 offset:53248
	ds_read_b128 v[184:187], v228 offset:54272
	ds_read_b128 v[188:191], v228 offset:55296
	ds_read_b128 v[192:195], v228 offset:56320
	global_load_lds_dwordx4 v[214:215], off
	s_add_i32 m0, s40, 0x2000
	s_add_u32 s38, s38, 0x80080
	v_lshl_add_u64 v[214:215], v[216:217], 0, s[12:13]
	s_addc_u32 s39, s39, 0
	s_add_i32 s40, s65, s47
	global_load_lds_dwordx4 v[214:215], off
	s_mov_b32 m0, s40
	v_lshl_add_u64 v[214:215], s[38:39], 0, v[0:1]
	global_load_lds_dwordx4 v[214:215], off
	s_add_i32 m0, s40, 0x2000
	v_lshl_add_u64 v[214:215], s[38:39], 0, v[208:209]
	global_load_lds_dwordx4 v[214:215], off
	s_mov_b32 m0, s55
	v_lshl_add_u64 v[214:215], v[218:219], 0, s[12:13]
	global_load_lds_dwordx4 v[214:215], off
	s_mov_b32 m0, s56
	v_lshl_add_u64 v[214:215], v[220:221], 0, s[12:13]
	global_load_lds_dwordx4 v[214:215], off
	s_waitcnt vmcnt(8)
	s_waitcnt lgkmcnt(0)
	v_mfma_f32_16x16x32_f16 v[64:67], v[132:135], v[164:167], v[64:67]
	v_mfma_f32_16x16x32_f16 v[60:63], v[140:143], v[164:167], v[60:63]
	v_mfma_f32_16x16x32_f16 v[48:51], v[132:135], v[172:175], v[48:51]
	v_mfma_f32_16x16x32_f16 v[44:47], v[140:143], v[172:175], v[44:47]
	s_barrier
	s_setprio 1
	v_mfma_f32_16x16x32_f16 v[32:35], v[132:135], v[180:183], v[32:35]
	v_mfma_f32_16x16x32_f16 v[28:31], v[140:143], v[180:183], v[28:31]
	v_mfma_f32_16x16x32_f16 v[12:15], v[132:135], v[188:191], v[12:15]
	v_mfma_f32_16x16x32_f16 v[16:19], v[140:143], v[188:191], v[16:19]
	v_mfma_f32_16x16x32_f16 v[64:67], v[136:139], v[168:171], v[64:67]
	v_mfma_f32_16x16x32_f16 v[60:63], v[144:147], v[168:171], v[60:63]
	v_mfma_f32_16x16x32_f16 v[48:51], v[136:139], v[176:179], v[48:51]
	v_mfma_f32_16x16x32_f16 v[44:47], v[144:147], v[176:179], v[44:47]
	v_mfma_f32_16x16x32_f16 v[32:35], v[136:139], v[184:187], v[32:35]
	v_mfma_f32_16x16x32_f16 v[28:31], v[144:147], v[184:187], v[28:31]
	v_mfma_f32_16x16x32_f16 v[12:15], v[136:139], v[192:195], v[12:15]
	v_mfma_f32_16x16x32_f16 v[16:19], v[144:147], v[192:195], v[16:19]
	v_mfma_f32_16x16x32_f16 v[56:59], v[148:151], v[164:167], v[56:59]
	v_mfma_f32_16x16x32_f16 v[52:55], v[156:159], v[164:167], v[52:55]
	v_mfma_f32_16x16x32_f16 v[40:43], v[148:151], v[172:175], v[40:43]
	v_mfma_f32_16x16x32_f16 v[36:39], v[156:159], v[172:175], v[36:39]
	v_mfma_f32_16x16x32_f16 v[24:27], v[148:151], v[180:183], v[24:27]
	v_mfma_f32_16x16x32_f16 v[20:23], v[156:159], v[180:183], v[20:23]
	v_mfma_f32_16x16x32_f16 v[4:7], v[148:151], v[188:191], v[4:7]
	v_mfma_f32_16x16x32_f16 v[8:11], v[156:159], v[188:191], v[8:11]
	v_mfma_f32_16x16x32_f16 v[56:59], v[152:155], v[168:171], v[56:59]
	v_mfma_f32_16x16x32_f16 v[52:55], v[160:163], v[168:171], v[52:55]
	v_mfma_f32_16x16x32_f16 v[40:43], v[152:155], v[176:179], v[40:43]
	v_mfma_f32_16x16x32_f16 v[36:39], v[160:163], v[176:179], v[36:39]
	v_mfma_f32_16x16x32_f16 v[24:27], v[152:155], v[184:187], v[24:27]
	v_mfma_f32_16x16x32_f16 v[20:23], v[160:163], v[184:187], v[20:23]
	v_mfma_f32_16x16x32_f16 v[4:7], v[152:155], v[192:195], v[4:7]
	v_mfma_f32_16x16x32_f16 v[8:11], v[160:163], v[192:195], v[8:11]
	s_setprio 0
	s_barrier
	s_add_i32 s63, s63, 2
	s_add_u32 s61, s61, 0x100
	s_addc_u32 s62, s62, 0
	s_add_u32 s36, s36, 0x100
	s_addc_u32 s37, s37, 0
	s_cmp_gt_u32 s63, 29
	s_cbranch_scc0 .LBB0_342
	s_and_b64 vcc, exec, s[14:15]
	s_cbranch_vccz .LBB0_345
	s_barrier

; #define PG8_STAGE(bufoff, gbase, voff) do { _Pragma("unroll") for (int _i = 0; _i < 2; ++_i) \
;         __builtin_amdgcn_global_load_lds((const unsigned*)((const char*)(gbase) + (voff)[_i]), (LAS unsigned*)(lds + (bufoff) + ldsw + _i * 8192), 16, 0, 0); } while (0)
; #define PG8_LDA(dst, b, h) do { _Pragma("unroll") for (int m = 0; m < 4; ++m) _Pragma("unroll") for (int k = 0; k < 2; ++k) dst[m][k] = *(const LAS bf16x8*)(lds + PG8_SA(b, h) + aoff + m * 2048 + k * 1024); } while (0)
; #define PG8_LDB(dst, b, h) do { _Pragma("unroll") for (int n = 0; n < 2; ++n) _Pragma("unroll") for (int k = 0; k < 2; ++k) dst[n][k] = *(const LAS bf16x8*)(lds + PG8_SB(b, h) + boff + n * 2048 + k * 1024); } while (0)
; #define PG8_WAIT_V(n) asm volatile("s_waitcnt vmcnt(" #n ")" ::: "memory")
; #define PG8_WAIT_L(n) asm volatile("s_waitcnt lgkmcnt(" #n ")" ::: "memory")
; #define PG8_BAR __builtin_amdgcn_s_barrier()
; #define PG8_SCHED __builtin_amdgcn_sched_barrier(0)
; template <class Epi, class Sched, bool FUSED = false, bool APERM = false>
; __device__ __forceinline__ void gemm_phase(int wid_s, LAS unsigned char* lds, const Gemm g, const Sched& S, const Epi& E) {
;     ...
;         for (int t = 0; t < nt; t += 2) {
;             const bool last = (t == nt - 2);
;             const char* a1 = cA + (size_t)(t + 1) * kstep;
;             const char* a2 = last ? nA : cA + (size_t)(t + 2) * kstep; const char* b2 = last ? nB : cB + (size_t)(t + 2) * kstep;
;             const char* a3 = a2 + kstep; const char* b3 = b2 + kstep;
;             if (last && has_next) S.a_ready(nxt);
;             PG8_LDB(B0, 0, 0); PG8_LDB(B1, 0, 1); PG8_SCHED; PG8_LDA(At, 0, 0); PG8_STAGE(PG8_SA(1, 1), a1 + hstep, voffA);
;             PG8_WAIT_V(8); PG8_WAIT_L(0); PG8_BAR; PG8_MMA(0, 0, At, B0); PG8_MMA(0, 1, At, B1); PG8_BAR; PG8_SCHED;
;             PG8_LDA(At, 0, 1); PG8_STAGE(PG8_SB(0, 0), b2, voffB); PG8_STAGE(PG8_SB(0, 1), b2 + hstep, voffB); PG8_STAGE(PG8_SA(0, 0), a2, voffA);
;             PG8_WAIT_V(8); PG8_WAIT_L(0); PG8_BAR; PG8_MMA(1, 0, At, B0); PG8_MMA(1, 1, At, B1); PG8_BAR; PG8_SCHED;
.LBB0_582:
	s_add_u32 s24, s22, 0xfffe0080
	s_addc_u32 s25, s23, -1
	s_add_i32 s50, 0, 0x10000
	s_cmp_eq_u32 s49, 4
	s_cselect_b32 s27, s15, s25
	s_cselect_b32 s26, s45, s24
	v_add_u32_e32 v141, s50, v139
	s_cselect_b32 s25, s9, s48
	s_cselect_b32 s24, s46, s47
	s_add_i32 s52, 0, 0x14000
	ds_read_b128 v[142:145], v141
	ds_read_b128 v[146:149], v141 offset:1024
	ds_read_b128 v[150:153], v141 offset:2048
	ds_read_b128 v[154:157], v141 offset:3072
	v_add_u32_e32 v141, s52, v139
	ds_read_b128 v[158:161], v141
	ds_read_b128 v[162:165], v141 offset:1024
	ds_read_b128 v[166:169], v141 offset:2048
	ds_read_b128 v[170:173], v141 offset:3072
	v_lshl_add_u64 v[194:195], s[22:23], 0, v[136:137]
	s_add_i32 m0, s21, 0xc000
	ds_read_b128 v[174:177], v140
	ds_read_b128 v[178:181], v140 offset:1024
	ds_read_b128 v[182:185], v140 offset:2048
	ds_read_b128 v[186:189], v140 offset:3072
	ds_read_b128 v[190:193], v140 offset:4096
	ds_read_b128 v[208:211], v140 offset:5120
	ds_read_b128 v[212:215], v140 offset:6144
	ds_read_b128 v[216:219], v140 offset:7168
	global_load_lds_dwordx4 v[194:195], off
	s_add_i32 m0, s21, 0xe000
	v_lshl_add_u64 v[194:195], s[22:23], 0, v[134:135]
	global_load_lds_dwordx4 v[194:195], off
	s_waitcnt vmcnt(8)
	s_waitcnt lgkmcnt(0)
	v_mfma_f32_16x16x32_f16 v[128:131], v[142:145], v[174:177], v[128:131]
	v_mfma_f32_16x16x32_f16 v[120:123], v[150:153], v[174:177], v[120:123]
	v_mfma_f32_16x16x32_f16 v[112:115], v[142:145], v[182:185], v[112:115]
	v_mfma_f32_16x16x32_f16 v[104:107], v[150:153], v[182:185], v[104:107]
	s_barrier
	s_setprio 1
	v_mfma_f32_16x16x32_f16 v[96:99], v[142:145], v[190:193], v[96:99]
	v_mfma_f32_16x16x32_f16 v[88:91], v[150:153], v[190:193], v[88:91]
	v_mfma_f32_16x16x32_f16 v[80:83], v[142:145], v[212:215], v[80:83]
	v_mfma_f32_16x16x32_f16 v[72:75], v[150:153], v[212:215], v[72:75]
	v_mfma_f32_16x16x32_f16 v[128:131], v[146:149], v[178:181], v[128:131]
	v_mfma_f32_16x16x32_f16 v[120:123], v[154:157], v[178:181], v[120:123]
	v_mfma_f32_16x16x32_f16 v[112:115], v[146:149], v[186:189], v[112:115]
	v_mfma_f32_16x16x32_f16 v[104:107], v[154:157], v[186:189], v[104:107]
	v_mfma_f32_16x16x32_f16 v[96:99], v[146:149], v[208:211], v[96:99]
	v_mfma_f32_16x16x32_f16 v[88:91], v[154:157], v[208:211], v[88:91]
	v_mfma_f32_16x16x32_f16 v[80:83], v[146:149], v[216:219], v[80:83]
	v_mfma_f32_16x16x32_f16 v[72:75], v[154:157], v[216:219], v[72:75]
	v_mfma_f32_16x16x32_f16 v[124:127], v[158:161], v[174:177], v[124:127]
	v_mfma_f32_16x16x32_f16 v[116:119], v[166:169], v[174:177], v[116:119]
	v_mfma_f32_16x16x32_f16 v[108:111], v[158:161], v[182:185], v[108:111]
	v_mfma_f32_16x16x32_f16 v[100:103], v[166:169], v[182:185], v[100:103]
	v_mfma_f32_16x16x32_f16 v[92:95], v[158:161], v[190:193], v[92:95]
	v_mfma_f32_16x16x32_f16 v[84:87], v[166:169], v[190:193], v[84:87]
	v_mfma_f32_16x16x32_f16 v[76:79], v[158:161], v[212:215], v[76:79]
	v_mfma_f32_16x16x32_f16 v[68:71], v[166:169], v[212:215], v[68:71]
	v_mfma_f32_16x16x32_f16 v[124:127], v[162:165], v[178:181], v[124:127]
	v_mfma_f32_16x16x32_f16 v[116:119], v[170:173], v[178:181], v[116:119]
	v_mfma_f32_16x16x32_f16 v[108:111], v[162:165], v[186:189], v[108:111]
	v_mfma_f32_16x16x32_f16 v[100:103], v[170:173], v[186:189], v[100:103]
	v_mfma_f32_16x16x32_f16 v[92:95], v[162:165], v[208:211], v[92:95]
	v_mfma_f32_16x16x32_f16 v[84:87], v[170:173], v[208:211], v[84:87]
	v_mfma_f32_16x16x32_f16 v[76:79], v[162:165], v[216:219], v[76:79]
	v_mfma_f32_16x16x32_f16 v[68:71], v[170:173], v[216:219], v[68:71]
	s_setprio 0
	s_barrier
	s_add_i32 s50, s50, s36
	v_lshl_add_u64 v[194:195], s[24:25], 0, v[0:1]
	s_mov_b32 m0, s50
	ds_read_b128 v[174:177], v140 offset:16384
	ds_read_b128 v[178:181], v140 offset:17408
	ds_read_b128 v[182:185], v140 offset:18432
	ds_read_b128 v[186:189], v140 offset:19456
	ds_read_b128 v[190:193], v140 offset:20480
	ds_read_b128 v[208:211], v140 offset:21504
	ds_read_b128 v[212:215], v140 offset:22528
	ds_read_b128 v[216:219], v140 offset:23552
	global_load_lds_dwordx4 v[194:195], off
	s_add_i32 m0, s50, 0x2000
	s_add_u32 s50, s24, 0x20000
	v_lshl_add_u64 v[220:221], s[24:25], 0, v[132:133]
	s_addc_u32 s51, s25, 0
	s_add_i32 s52, s52, s36
	global_load_lds_dwordx4 v[220:221], off
	v_lshl_add_u64 v[222:223], s[50:51], 0, v[0:1]
	s_mov_b32 m0, s52
	v_lshl_add_u64 v[224:225], s[26:27], 0, v[132:133]
	global_load_lds_dwordx4 v[222:223], off
	s_add_i32 m0, s52, 0x2000
	v_lshl_add_u64 v[222:223], s[50:51], 0, v[132:133]
	global_load_lds_dwordx4 v[222:223], off
	s_mov_b32 m0, s21
	v_lshl_add_u64 v[222:223], s[26:27], 0, v[0:1]
	global_load_lds_dwordx4 v[222:223], off
	s_mov_b32 m0, s37
	s_nop 0
	global_load_lds_dwordx4 v[224:225], off
	s_waitcnt vmcnt(8)
	s_waitcnt lgkmcnt(0)
	v_mfma_f32_16x16x32_f16 v[64:67], v[142:145], v[174:177], v[64:67]
	v_mfma_f32_16x16x32_f16 v[56:59], v[150:153], v[174:177], v[56:59]
	v_mfma_f32_16x16x32_f16 v[48:51], v[142:145], v[182:185], v[48:51]
	v_mfma_f32_16x16x32_f16 v[40:43], v[150:153], v[182:185], v[40:43]
	s_barrier
; #define PG8_STAGE(bufoff, gbase, voff) do { _Pragma("unroll") for (int _i = 0; _i < 2; ++_i) \
;         __builtin_amdgcn_global_load_lds((const unsigned*)((const char*)(gbase) + (voff)[_i]), (LAS unsigned*)(lds + (bufoff) + ldsw + _i * 8192), 16, 0, 0); } while (0)
; #define PG8_LDA(dst, b, h) do { _Pragma("unroll") for (int m = 0; m < 4; ++m) _Pragma("unroll") for (int k = 0; k < 2; ++k) dst[m][k] = *(const LAS bf16x8*)(lds + PG8_SA(b, h) + aoff + m * 2048 + k * 1024); } while (0)
; #define PG8_LDB(dst, b, h) do { _Pragma("unroll") for (int n = 0; n < 2; ++n) _Pragma("unroll") for (int k = 0; k < 2; ++k) dst[n][k] = *(const LAS bf16x8*)(lds + PG8_SB(b, h) + boff + n * 2048 + k * 1024); } while (0)
; #define PG8_WAIT_V(n) asm volatile("s_waitcnt vmcnt(" #n ")" ::: "memory")
; #define PG8_WAIT_L(n) asm volatile("s_waitcnt lgkmcnt(" #n ")" ::: "memory")
; #define PG8_BAR __builtin_amdgcn_s_barrier()
; #define PG8_SCHED __builtin_amdgcn_sched_barrier(0)
; template <class Epi, class Sched, bool FUSED = false, bool APERM = false>
; __device__ __forceinline__ void gemm_phase(int wid_s, LAS unsigned char* lds, const Gemm g, const Sched& S, const Epi& E) {
;     ...
;             PG8_WAIT_V(8); PG8_WAIT_L(0); PG8_BAR; PG8_MMA(1, 0, At, B0); PG8_MMA(1, 1, At, B1); PG8_BAR; PG8_SCHED;
;             PG8_LDB(B0, 1, 0); PG8_LDB(B1, 1, 1); PG8_SCHED; PG8_LDA(At, 1, 0); PG8_STAGE(PG8_SA(0, 1), a2 + hstep, voffA);
;             PG8_WAIT_V(8); PG8_WAIT_L(0); PG8_BAR; PG8_MMA(0, 0, At, B0); PG8_MMA(0, 1, At, B1); PG8_BAR; PG8_SCHED;
	s_setprio 1
	v_mfma_f32_16x16x32_f16 v[32:35], v[142:145], v[190:193], v[32:35]
	v_mfma_f32_16x16x32_f16 v[24:27], v[150:153], v[190:193], v[24:27]
	v_mfma_f32_16x16x32_f16 v[16:19], v[142:145], v[212:215], v[16:19]
	v_mfma_f32_16x16x32_f16 v[8:11], v[150:153], v[212:215], v[8:11]
	v_mfma_f32_16x16x32_f16 v[64:67], v[146:149], v[178:181], v[64:67]
	v_mfma_f32_16x16x32_f16 v[56:59], v[154:157], v[178:181], v[56:59]
	v_mfma_f32_16x16x32_f16 v[48:51], v[146:149], v[186:189], v[48:51]
	v_mfma_f32_16x16x32_f16 v[40:43], v[154:157], v[186:189], v[40:43]
	v_mfma_f32_16x16x32_f16 v[32:35], v[146:149], v[208:211], v[32:35]
	v_mfma_f32_16x16x32_f16 v[24:27], v[154:157], v[208:211], v[24:27]
	v_mfma_f32_16x16x32_f16 v[16:19], v[146:149], v[216:219], v[16:19]
	v_mfma_f32_16x16x32_f16 v[8:11], v[154:157], v[216:219], v[8:11]
	v_mfma_f32_16x16x32_f16 v[60:63], v[158:161], v[174:177], v[60:63]
	v_mfma_f32_16x16x32_f16 v[52:55], v[166:169], v[174:177], v[52:55]
	v_mfma_f32_16x16x32_f16 v[44:47], v[158:161], v[182:185], v[44:47]
	v_mfma_f32_16x16x32_f16 v[36:39], v[166:169], v[182:185], v[36:39]
	v_mfma_f32_16x16x32_f16 v[28:31], v[158:161], v[190:193], v[28:31]
	v_mfma_f32_16x16x32_f16 v[20:23], v[166:169], v[190:193], v[20:23]
	v_mfma_f32_16x16x32_f16 v[12:15], v[158:161], v[212:215], v[12:15]
	v_mfma_f32_16x16x32_f16 v[4:7], v[166:169], v[212:215], v[4:7]
	v_mfma_f32_16x16x32_f16 v[60:63], v[162:165], v[178:181], v[60:63]
	v_mfma_f32_16x16x32_f16 v[52:55], v[170:173], v[178:181], v[52:55]
	v_mfma_f32_16x16x32_f16 v[44:47], v[162:165], v[186:189], v[44:47]
	v_mfma_f32_16x16x32_f16 v[36:39], v[170:173], v[186:189], v[36:39]
	v_mfma_f32_16x16x32_f16 v[28:31], v[162:165], v[208:211], v[28:31]
	v_mfma_f32_16x16x32_f16 v[20:23], v[170:173], v[208:211], v[20:23]
	v_mfma_f32_16x16x32_f16 v[12:15], v[162:165], v[216:219], v[12:15]
	v_mfma_f32_16x16x32_f16 v[4:7], v[170:173], v[216:219], v[4:7]
	s_setprio 0
	s_barrier
	s_add_i32 s50, 0, 0x18000
	v_add_u32_e32 v141, s50, v139
	s_add_i32 s51, 0, 0x1c000
	ds_read_b128 v[142:145], v141
	ds_read_b128 v[146:149], v141 offset:1024
	ds_read_b128 v[150:153], v141 offset:2048
	ds_read_b128 v[154:157], v141 offset:3072
	v_add_u32_e32 v141, s51, v139
	ds_read_b128 v[158:161], v141
	ds_read_b128 v[162:165], v141 offset:1024
	ds_read_b128 v[166:169], v141 offset:2048
	ds_read_b128 v[170:173], v141 offset:3072
	s_add_u32 s26, s26, 0x20000
	s_addc_u32 s27, s27, 0
	s_mov_b32 m0, s38
	v_lshl_add_u64 v[226:227], s[26:27], 0, v[0:1]
	ds_read_b128 v[174:177], v140 offset:32768
	ds_read_b128 v[178:181], v140 offset:33792
	ds_read_b128 v[182:185], v140 offset:34816
	ds_read_b128 v[186:189], v140 offset:35840
	ds_read_b128 v[190:193], v140 offset:36864
	ds_read_b128 v[208:211], v140 offset:37888
	ds_read_b128 v[212:215], v140 offset:38912
	ds_read_b128 v[216:219], v140 offset:39936
	global_load_lds_dwordx4 v[226:227], off
	s_mov_b32 m0, s39
	v_lshl_add_u64 v[226:227], s[26:27], 0, v[132:133]
	global_load_lds_dwordx4 v[226:227], off
	s_waitcnt vmcnt(8)
	s_waitcnt lgkmcnt(0)
	v_mfma_f32_16x16x32_f16 v[128:131], v[142:145], v[174:177], v[128:131]
	v_mfma_f32_16x16x32_f16 v[120:123], v[150:153], v[174:177], v[120:123]
	v_mfma_f32_16x16x32_f16 v[112:115], v[142:145], v[182:185], v[112:115]
	v_mfma_f32_16x16x32_f16 v[104:107], v[150:153], v[182:185], v[104:107]
	s_barrier
	s_setprio 1
	v_mfma_f32_16x16x32_f16 v[96:99], v[142:145], v[190:193], v[96:99]
	v_mfma_f32_16x16x32_f16 v[88:91], v[150:153], v[190:193], v[88:91]
	v_mfma_f32_16x16x32_f16 v[80:83], v[142:145], v[212:215], v[80:83]
	v_mfma_f32_16x16x32_f16 v[72:75], v[150:153], v[212:215], v[72:75]
	v_mfma_f32_16x16x32_f16 v[128:131], v[146:149], v[178:181], v[128:131]
	v_mfma_f32_16x16x32_f16 v[120:123], v[154:157], v[178:181], v[120:123]
	v_mfma_f32_16x16x32_f16 v[112:115], v[146:149], v[186:189], v[112:115]
	v_mfma_f32_16x16x32_f16 v[104:107], v[154:157], v[186:189], v[104:107]
	v_mfma_f32_16x16x32_f16 v[96:99], v[146:149], v[208:211], v[96:99]
	v_mfma_f32_16x16x32_f16 v[88:91], v[154:157], v[208:211], v[88:91]
	v_mfma_f32_16x16x32_f16 v[80:83], v[146:149], v[216:219], v[80:83]
	v_mfma_f32_16x16x32_f16 v[72:75], v[154:157], v[216:219], v[72:75]
	v_mfma_f32_16x16x32_f16 v[124:127], v[158:161], v[174:177], v[124:127]
	v_mfma_f32_16x16x32_f16 v[116:119], v[166:169], v[174:177], v[116:119]
	v_mfma_f32_16x16x32_f16 v[108:111], v[158:161], v[182:185], v[108:111]
	v_mfma_f32_16x16x32_f16 v[100:103], v[166:169], v[182:185], v[100:103]
	v_mfma_f32_16x16x32_f16 v[92:95], v[158:161], v[190:193], v[92:95]
	v_mfma_f32_16x16x32_f16 v[84:87], v[166:169], v[190:193], v[84:87]
	v_mfma_f32_16x16x32_f16 v[76:79], v[158:161], v[212:215], v[76:79]
	v_mfma_f32_16x16x32_f16 v[68:71], v[166:169], v[212:215], v[68:71]
	v_mfma_f32_16x16x32_f16 v[124:127], v[162:165], v[178:181], v[124:127]
	v_mfma_f32_16x16x32_f16 v[116:119], v[170:173], v[178:181], v[116:119]
	v_mfma_f32_16x16x32_f16 v[108:111], v[162:165], v[186:189], v[108:111]
	v_mfma_f32_16x16x32_f16 v[100:103], v[170:173], v[186:189], v[100:103]
	v_mfma_f32_16x16x32_f16 v[92:95], v[162:165], v[208:211], v[92:95]
	v_mfma_f32_16x16x32_f16 v[84:87], v[170:173], v[208:211], v[84:87]
	v_mfma_f32_16x16x32_f16 v[76:79], v[162:165], v[216:219], v[76:79]
	v_mfma_f32_16x16x32_f16 v[68:71], v[170:173], v[216:219], v[68:71]
	s_setprio 0
	s_barrier
; #define PG8_STAGE(bufoff, gbase, voff) do { _Pragma("unroll") for (int _i = 0; _i < 2; ++_i) \
;         __builtin_amdgcn_global_load_lds((const unsigned*)((const char*)(gbase) + (voff)[_i]), (LAS unsigned*)(lds + (bufoff) + ldsw + _i * 8192), 16, 0, 0); } while (0)
; #define PG8_LDA(dst, b, h) do { _Pragma("unroll") for (int m = 0; m < 4; ++m) _Pragma("unroll") for (int k = 0; k < 2; ++k) dst[m][k] = *(const LAS bf16x8*)(lds + PG8_SA(b, h) + aoff + m * 2048 + k * 1024); } while (0)
; #define PG8_WAIT_V(n) asm volatile("s_waitcnt vmcnt(" #n ")" ::: "memory")
; #define PG8_WAIT_L(n) asm volatile("s_waitcnt lgkmcnt(" #n ")" ::: "memory")
; #define PG8_BAR __builtin_amdgcn_s_barrier()
; #define PG8_SCHED __builtin_amdgcn_sched_barrier(0)
; template <class Epi, class Sched, bool FUSED = false, bool APERM = false>
; __device__ __forceinline__ void gemm_phase(int wid_s, LAS unsigned char* lds, const Gemm g, const Sched& S, const Epi& E) {
;     ...
;             PG8_WAIT_V(8); PG8_WAIT_L(0); PG8_BAR; PG8_MMA(0, 0, At, B0); PG8_MMA(0, 1, At, B1); PG8_BAR; PG8_SCHED;
;             PG8_LDA(At, 1, 1); PG8_STAGE(PG8_SB(1, 0), b3, voffB); PG8_STAGE(PG8_SB(1, 1), b3 + hstep, voffB); PG8_STAGE(PG8_SA(1, 0), a3, voffA);
;             PG8_WAIT_V(8); PG8_WAIT_L(0); PG8_BAR; PG8_MMA(1, 0, At, B0); PG8_MMA(1, 1, At, B1); PG8_BAR; PG8_SCHED;
;         }
;         if (wr == 0) PG8_BAR;
	s_add_i32 s26, s50, s36
	v_lshl_add_u64 v[194:195], v[194:195], 0, s[12:13]
	s_mov_b32 m0, s26
	ds_read_b128 v[174:177], v140 offset:49152
	ds_read_b128 v[178:181], v140 offset:50176
	ds_read_b128 v[182:185], v140 offset:51200
	ds_read_b128 v[186:189], v140 offset:52224
	ds_read_b128 v[190:193], v140 offset:53248
	ds_read_b128 v[208:211], v140 offset:54272
	ds_read_b128 v[212:215], v140 offset:55296
	ds_read_b128 v[216:219], v140 offset:56320
	global_load_lds_dwordx4 v[194:195], off
	s_add_i32 m0, s26, 0x2000
	s_add_u32 s24, s24, 0x20080
	v_lshl_add_u64 v[194:195], v[220:221], 0, s[12:13]
	s_addc_u32 s25, s25, 0
	s_add_i32 s26, s51, s36
	global_load_lds_dwordx4 v[194:195], off
	s_mov_b32 m0, s26
	v_lshl_add_u64 v[194:195], s[24:25], 0, v[0:1]
	global_load_lds_dwordx4 v[194:195], off
	s_add_i32 m0, s26, 0x2000
	v_lshl_add_u64 v[194:195], s[24:25], 0, v[132:133]
	global_load_lds_dwordx4 v[194:195], off
	s_mov_b32 m0, s41
	v_lshl_add_u64 v[194:195], v[222:223], 0, s[12:13]
	global_load_lds_dwordx4 v[194:195], off
	s_mov_b32 m0, s42
	v_lshl_add_u64 v[194:195], v[224:225], 0, s[12:13]
	global_load_lds_dwordx4 v[194:195], off
	s_waitcnt vmcnt(8)
	s_waitcnt lgkmcnt(0)
	v_mfma_f32_16x16x32_f16 v[64:67], v[142:145], v[174:177], v[64:67]
	v_mfma_f32_16x16x32_f16 v[56:59], v[150:153], v[174:177], v[56:59]
	v_mfma_f32_16x16x32_f16 v[48:51], v[142:145], v[182:185], v[48:51]
	v_mfma_f32_16x16x32_f16 v[40:43], v[150:153], v[182:185], v[40:43]
	s_barrier
	s_setprio 1
	v_mfma_f32_16x16x32_f16 v[32:35], v[142:145], v[190:193], v[32:35]
	v_mfma_f32_16x16x32_f16 v[24:27], v[150:153], v[190:193], v[24:27]
	v_mfma_f32_16x16x32_f16 v[16:19], v[142:145], v[212:215], v[16:19]
	v_mfma_f32_16x16x32_f16 v[8:11], v[150:153], v[212:215], v[8:11]
	v_mfma_f32_16x16x32_f16 v[64:67], v[146:149], v[178:181], v[64:67]
	v_mfma_f32_16x16x32_f16 v[56:59], v[154:157], v[178:181], v[56:59]
	v_mfma_f32_16x16x32_f16 v[48:51], v[146:149], v[186:189], v[48:51]
	v_mfma_f32_16x16x32_f16 v[40:43], v[154:157], v[186:189], v[40:43]
	v_mfma_f32_16x16x32_f16 v[32:35], v[146:149], v[208:211], v[32:35]
	v_mfma_f32_16x16x32_f16 v[24:27], v[154:157], v[208:211], v[24:27]
	v_mfma_f32_16x16x32_f16 v[16:19], v[146:149], v[216:219], v[16:19]
	v_mfma_f32_16x16x32_f16 v[8:11], v[154:157], v[216:219], v[8:11]
	v_mfma_f32_16x16x32_f16 v[60:63], v[158:161], v[174:177], v[60:63]
	v_mfma_f32_16x16x32_f16 v[52:55], v[166:169], v[174:177], v[52:55]
	v_mfma_f32_16x16x32_f16 v[44:47], v[158:161], v[182:185], v[44:47]
	v_mfma_f32_16x16x32_f16 v[36:39], v[166:169], v[182:185], v[36:39]
	v_mfma_f32_16x16x32_f16 v[28:31], v[158:161], v[190:193], v[28:31]
	v_mfma_f32_16x16x32_f16 v[20:23], v[166:169], v[190:193], v[20:23]
	v_mfma_f32_16x16x32_f16 v[12:15], v[158:161], v[212:215], v[12:15]
	v_mfma_f32_16x16x32_f16 v[4:7], v[166:169], v[212:215], v[4:7]
	v_mfma_f32_16x16x32_f16 v[60:63], v[162:165], v[178:181], v[60:63]
	v_mfma_f32_16x16x32_f16 v[52:55], v[170:173], v[178:181], v[52:55]
	v_mfma_f32_16x16x32_f16 v[44:47], v[162:165], v[186:189], v[44:47]
	v_mfma_f32_16x16x32_f16 v[36:39], v[170:173], v[186:189], v[36:39]
	v_mfma_f32_16x16x32_f16 v[28:31], v[162:165], v[208:211], v[28:31]
	v_mfma_f32_16x16x32_f16 v[20:23], v[170:173], v[208:211], v[20:23]
	v_mfma_f32_16x16x32_f16 v[12:15], v[162:165], v[216:219], v[12:15]
	v_mfma_f32_16x16x32_f16 v[4:7], v[170:173], v[216:219], v[4:7]
	s_setprio 0
	s_barrier
	s_add_i32 s49, s49, 2
	s_add_u32 s47, s47, 0x100
	s_addc_u32 s48, s48, 0
	s_add_u32 s22, s22, 0x100
	s_addc_u32 s23, s23, 0
	s_cmp_gt_u32 s49, 5
	s_cbranch_scc0 .LBB0_582
	s_and_b64 vcc, exec, s[6:7]
	s_cbranch_vccz .LBB0_585
	s_barrier
